# same trims as v037 but the static priority raise on waves 0-3 instead of 4-7
# baseline (speedup 1.0000x reference)
; #define LAS __attribute__((address_space(3)))
; __global__ void __launch_bounds__(NTHREADS, 2) mk_fwd(Params P_arg) {
;     extern __shared__ __attribute__((aligned(16))) unsigned char lds_raw[];
;     LAS unsigned char* lds = (LAS unsigned char*)lds_raw;
;     cg::grid_group grid = cg::this_grid();
;     volatile LAS unsigned* bar_st = (volatile LAS unsigned*)(lds + LDS_BYTES - 64);
;     if (threadIdx.x == 0) { bar_st[0] = 0u; bar_st[1] = 0u; }
;     __syncthreads();
_Z6mk_fwd6Params:
	v_readfirstlane_b32 s98, v0
	s_nop 3
	s_and_b32 s98, s98, 0x3ff
	s_lshr_b32 s98, s98, 6
	s_cmp_ge_u32 s98, 4
	s_cbranch_scc1 .Lsprio_skip
	s_setprio 1
